# stack19: stack18 + V-cache conversion of each layer moved from the conversion phase into the input-projection tail (spare CUs), done as a 64x64 wave-private LDS transpose with dwordx4 loads and 128-by
# speedup vs baseline: 1.0312x; 1.0158x over previous
.LBB0_589:
	s_cmp_gt_u32 s90, 0xa6
	s_cselect_b32 s36, 0xa6, 0
	s_cmp_lt_u32 s21, s36
	s_cbranch_scc1 .Lvt_done
	v_readlane_b32 s37, v250, 58
	v_readlane_b32 s38, v250, 52
	v_readlane_b32 s39, v250, 53
	v_readfirstlane_b32 s40, v224
	v_and_b32_e32 v0, 63, v224
	s_lshr_b32 s40, s40, 6
	s_mul_i32 s62, s40, 0x2400
	s_sub_u32 s41, s21, s36
	s_lshl_b32 s41, s41, 3
	s_add_u32 s40, s40, s41
	s_sub_u32 s41, s90, s36
	s_lshl_b32 s41, s41, 3
	s_load_dwordx2 s[46:47], s[38:39], 0x18
	v_lshrrev_b32_e32 v5, 4, v0
	v_and_b32_e32 v6, 15, v0
	v_lshlrev_b32_e32 v1, 11, v5
	v_lshl_add_u32 v1, v6, 4, v1
	v_mul_u32_u24_e32 v2, 0x240, v6
	v_lshl_add_u32 v2, v5, 1, v2
	v_add_u32_e32 v2, s62, v2
	v_lshrrev_b32_e32 v5, 3, v0
	v_and_b32_e32 v6, 7, v0
	v_mul_u32_u24_e32 v3, 0x90, v5
	v_lshl_add_u32 v3, v6, 4, v3
	v_add_u32_e32 v3, s62, v3
	v_mul_u32_u24_e32 v4, 0x2080, v5
	v_lshl_add_u32 v4, v6, 4, v4
	s_add_u32 s48, s96, 0x1a788000
	s_addc_u32 s49, s97, 0
	s_lshl_b32 s42, s37, 26
	s_waitcnt lgkmcnt(0)
	s_add_u32 s46, s46, s42
	s_addc_u32 s47, s47, 0
	s_mov_b32 s50, s40
.Lvt_loop:
	s_cmp_ge_u32 s50, 0x1000
	s_cbranch_scc1 .Lvt_done
	s_lshr_b32 s51, s50, 9
	s_bfe_u32 s52, s50, 0x60003
	s_and_b32 s53, s50, 7
	s_lshl_b32 s58, s51, 23
	s_lshl_b32 s54, s52, 17
	s_add_u32 s58, s58, s54
	s_lshl_b32 s54, s53, 8
	s_add_u32 s58, s58, s54
	s_add_u32 s58, s46, s58
	s_addc_u32 s59, s47, 0
	global_load_dwordx4 v[32:35], v1, s[58:59]
	s_add_u32 s58, s58, 0x2000
	s_addc_u32 s59, s59, 0
	global_load_dwordx4 v[36:39], v1, s[58:59]
	s_add_u32 s58, s58, 0x2000
	s_addc_u32 s59, s59, 0
	global_load_dwordx4 v[40:43], v1, s[58:59]
	s_add_u32 s58, s58, 0x2000
	s_addc_u32 s59, s59, 0
	global_load_dwordx4 v[44:47], v1, s[58:59]
	s_add_u32 s58, s58, 0x2000
	s_addc_u32 s59, s59, 0
	global_load_dwordx4 v[48:51], v1, s[58:59]
	s_add_u32 s58, s58, 0x2000
	s_addc_u32 s59, s59, 0
	global_load_dwordx4 v[52:55], v1, s[58:59]
	s_add_u32 s58, s58, 0x2000
	s_addc_u32 s59, s59, 0
	global_load_dwordx4 v[56:59], v1, s[58:59]
	s_add_u32 s58, s58, 0x2000
	s_addc_u32 s59, s59, 0
	global_load_dwordx4 v[60:63], v1, s[58:59]
	s_add_u32 s58, s58, 0x2000
	s_addc_u32 s59, s59, 0
	global_load_dwordx4 v[64:67], v1, s[58:59]
	s_add_u32 s58, s58, 0x2000
	s_addc_u32 s59, s59, 0
	global_load_dwordx4 v[68:71], v1, s[58:59]
	s_add_u32 s58, s58, 0x2000
	s_addc_u32 s59, s59, 0
	global_load_dwordx4 v[72:75], v1, s[58:59]
	s_add_u32 s58, s58, 0x2000
	s_addc_u32 s59, s59, 0
	global_load_dwordx4 v[76:79], v1, s[58:59]
	s_add_u32 s58, s58, 0x2000
	s_addc_u32 s59, s59, 0
	global_load_dwordx4 v[80:83], v1, s[58:59]
	s_add_u32 s58, s58, 0x2000
	s_addc_u32 s59, s59, 0
	global_load_dwordx4 v[84:87], v1, s[58:59]
	s_add_u32 s58, s58, 0x2000
	s_addc_u32 s59, s59, 0
	global_load_dwordx4 v[88:91], v1, s[58:59]
	s_add_u32 s58, s58, 0x2000
	s_addc_u32 s59, s59, 0
	global_load_dwordx4 v[92:95], v1, s[58:59]
	s_lshl_b32 s60, s51, 9
	s_lshl_b32 s54, s53, 6
	s_add_u32 s60, s60, s54
	s_mul_i32 s60, s60, 0x2080
	s_lshl_b32 s54, s52, 7
	s_add_u32 s60, s60, s54
	s_add_u32 s60, s48, s60
	s_addc_u32 s61, s49, 0
	s_waitcnt vmcnt(15)
	v_cvt_pk_bf16_f32 v32, v32, v33
	v_cvt_pk_bf16_f32 v33, v34, v35
	ds_write_b16 v2, v32 offset:0
	ds_write_b16_d16_hi v2, v32 offset:144
	ds_write_b16 v2, v33 offset:288
	ds_write_b16_d16_hi v2, v33 offset:432
	s_waitcnt vmcnt(14)
	v_cvt_pk_bf16_f32 v36, v36, v37
	v_cvt_pk_bf16_f32 v37, v38, v39
	ds_write_b16 v2, v36 offset:8
	ds_write_b16_d16_hi v2, v36 offset:152
	ds_write_b16 v2, v37 offset:296
	ds_write_b16_d16_hi v2, v37 offset:440
	s_waitcnt vmcnt(13)
	v_cvt_pk_bf16_f32 v40, v40, v41
	v_cvt_pk_bf16_f32 v41, v42, v43
	ds_write_b16 v2, v40 offset:16
	ds_write_b16_d16_hi v2, v40 offset:160
	ds_write_b16 v2, v41 offset:304
	ds_write_b16_d16_hi v2, v41 offset:448
	s_waitcnt vmcnt(12)
	v_cvt_pk_bf16_f32 v44, v44, v45
	v_cvt_pk_bf16_f32 v45, v46, v47
	ds_write_b16 v2, v44 offset:24
	ds_write_b16_d16_hi v2, v44 offset:168
	ds_write_b16 v2, v45 offset:312
	ds_write_b16_d16_hi v2, v45 offset:456
	s_waitcnt vmcnt(11)
	v_cvt_pk_bf16_f32 v48, v48, v49
	v_cvt_pk_bf16_f32 v49, v50, v51
	ds_write_b16 v2, v48 offset:32
	ds_write_b16_d16_hi v2, v48 offset:176
	ds_write_b16 v2, v49 offset:320
	ds_write_b16_d16_hi v2, v49 offset:464
	s_waitcnt vmcnt(10)
	v_cvt_pk_bf16_f32 v52, v52, v53
	v_cvt_pk_bf16_f32 v53, v54, v55
	ds_write_b16 v2, v52 offset:40
	ds_write_b16_d16_hi v2, v52 offset:184
	ds_write_b16 v2, v53 offset:328
	ds_write_b16_d16_hi v2, v53 offset:472
	s_waitcnt vmcnt(9)
	v_cvt_pk_bf16_f32 v56, v56, v57
	v_cvt_pk_bf16_f32 v57, v58, v59
	ds_write_b16 v2, v56 offset:48
	ds_write_b16_d16_hi v2, v56 offset:192
	ds_write_b16 v2, v57 offset:336
	ds_write_b16_d16_hi v2, v57 offset:480
	s_waitcnt vmcnt(8)
	v_cvt_pk_bf16_f32 v60, v60, v61
	v_cvt_pk_bf16_f32 v61, v62, v63
	ds_write_b16 v2, v60 offset:56
	ds_write_b16_d16_hi v2, v60 offset:200
	ds_write_b16 v2, v61 offset:344
	ds_write_b16_d16_hi v2, v61 offset:488
	s_waitcnt vmcnt(7)
	v_cvt_pk_bf16_f32 v64, v64, v65
	v_cvt_pk_bf16_f32 v65, v66, v67
	ds_write_b16 v2, v64 offset:64
	ds_write_b16_d16_hi v2, v64 offset:208
	ds_write_b16 v2, v65 offset:352
	ds_write_b16_d16_hi v2, v65 offset:496
	s_waitcnt vmcnt(6)
	v_cvt_pk_bf16_f32 v68, v68, v69
	v_cvt_pk_bf16_f32 v69, v70, v71
	ds_write_b16 v2, v68 offset:72
	ds_write_b16_d16_hi v2, v68 offset:216
	ds_write_b16 v2, v69 offset:360
	ds_write_b16_d16_hi v2, v69 offset:504
	s_waitcnt vmcnt(5)
	v_cvt_pk_bf16_f32 v72, v72, v73
	v_cvt_pk_bf16_f32 v73, v74, v75
	ds_write_b16 v2, v72 offset:80
	ds_write_b16_d16_hi v2, v72 offset:224
	ds_write_b16 v2, v73 offset:368
	ds_write_b16_d16_hi v2, v73 offset:512
	s_waitcnt vmcnt(4)
	v_cvt_pk_bf16_f32 v76, v76, v77
	v_cvt_pk_bf16_f32 v77, v78, v79
	ds_write_b16 v2, v76 offset:88
	ds_write_b16_d16_hi v2, v76 offset:232
	ds_write_b16 v2, v77 offset:376
	ds_write_b16_d16_hi v2, v77 offset:520
	s_waitcnt vmcnt(3)
	v_cvt_pk_bf16_f32 v80, v80, v81
	v_cvt_pk_bf16_f32 v81, v82, v83
	ds_write_b16 v2, v80 offset:96
	ds_write_b16_d16_hi v2, v80 offset:240
	ds_write_b16 v2, v81 offset:384
	ds_write_b16_d16_hi v2, v81 offset:528
	s_waitcnt vmcnt(2)
	v_cvt_pk_bf16_f32 v84, v84, v85
	v_cvt_pk_bf16_f32 v85, v86, v87
	ds_write_b16 v2, v84 offset:104
	ds_write_b16_d16_hi v2, v84 offset:248
	ds_write_b16 v2, v85 offset:392
	ds_write_b16_d16_hi v2, v85 offset:536
	s_waitcnt vmcnt(1)
	v_cvt_pk_bf16_f32 v88, v88, v89
	v_cvt_pk_bf16_f32 v89, v90, v91
	ds_write_b16 v2, v88 offset:112
	ds_write_b16_d16_hi v2, v88 offset:256
	ds_write_b16 v2, v89 offset:400
	ds_write_b16_d16_hi v2, v89 offset:544
	s_waitcnt vmcnt(0)
	v_cvt_pk_bf16_f32 v92, v92, v93
	v_cvt_pk_bf16_f32 v93, v94, v95
	ds_write_b16 v2, v92 offset:120
	ds_write_b16_d16_hi v2, v92 offset:264
	ds_write_b16 v2, v93 offset:408
	ds_write_b16_d16_hi v2, v93 offset:552
	s_waitcnt lgkmcnt(0)
	ds_read_b128 v[96:99], v3 offset:0
	ds_read_b128 v[100:103], v3 offset:1152
	ds_read_b128 v[104:107], v3 offset:2304
	ds_read_b128 v[108:111], v3 offset:3456
	ds_read_b128 v[112:115], v3 offset:4608
	ds_read_b128 v[116:119], v3 offset:5760
	ds_read_b128 v[120:123], v3 offset:6912
	ds_read_b128 v[124:127], v3 offset:8064
	s_waitcnt lgkmcnt(7)
	global_store_dwordx4 v4, v[96:99], s[60:61]
	s_add_u32 s60, s60, 0x10400
	s_addc_u32 s61, s61, 0
	s_waitcnt lgkmcnt(6)
	global_store_dwordx4 v4, v[100:103], s[60:61]
	s_add_u32 s60, s60, 0x10400
	s_addc_u32 s61, s61, 0
	s_waitcnt lgkmcnt(5)
	global_store_dwordx4 v4, v[104:107], s[60:61]
	s_add_u32 s60, s60, 0x10400
	s_addc_u32 s61, s61, 0
	s_waitcnt lgkmcnt(4)
	global_store_dwordx4 v4, v[108:111], s[60:61]
	s_add_u32 s60, s60, 0x10400
	s_addc_u32 s61, s61, 0
	s_waitcnt lgkmcnt(3)
	global_store_dwordx4 v4, v[112:115], s[60:61]
	s_add_u32 s60, s60, 0x10400
	s_addc_u32 s61, s61, 0
	s_waitcnt lgkmcnt(2)
	global_store_dwordx4 v4, v[116:119], s[60:61]
	s_add_u32 s60, s60, 0x10400
	s_addc_u32 s61, s61, 0
	s_waitcnt lgkmcnt(1)
	global_store_dwordx4 v4, v[120:123], s[60:61]
	s_add_u32 s60, s60, 0x10400
	s_addc_u32 s61, s61, 0
	s_waitcnt lgkmcnt(0)
	global_store_dwordx4 v4, v[124:127], s[60:61]
	s_add_u32 s50, s50, s41
	s_branch .Lvt_loop
